# stack + step A's reference-check blocks moved out of line (skip-mode path falls from the barrier into step B)
# speedup vs baseline: 1.0079x; 1.0079x over previous
.Lattn_fair_a:
	s_andn2_b32 s4, s99, s2
	s_cbranch_scc0 .LBB0_460
	v_add_f32_e32 v179, v198, v254

.LBB0_462:
	v_add_f32_e32 v179, v198, v254
	s_mov_b64 s[2:3], 0
	s_cmp_lg_u32 s99, 0
	s_cbranch_scc1 .LBB0_464
	s_nop 7
	v_max3_f32 v84, v98, v99, v114
	v_max3_f32 v85, v100, v101, v115
	s_nop 0
	v_max3_f32 v84, v84, v116, v117
	v_max3_f32 v85, v85, v104, v105
	s_nop 0
	v_max3_f32 v84, v84, v102, v103
	v_max3_f32 v85, v85, v120, v121
	s_nop 0
	v_max3_f32 v84, v84, v118, v119
	v_max3_f32 v85, v85, v108, v109
	s_nop 0
	v_max3_f32 v84, v84, v106, v107
	v_max3_f32 v85, v85, v124, v125
	s_nop 0
	v_max3_f32 v84, v84, v122, v123
	v_max3_f32 v85, v85, v112, v113
	s_nop 0
	v_max3_f32 v84, v84, v110, v111
	v_max3_f32 v85, v85, v128, v129
	s_nop 0
	v_max3_f32 v84, v84, v126, v127
	s_nop 0
	v_max_f32_e32 v84, v84, v85
	s_nop 0
	v_mov_b32_e32 v85, v84
	s_nop 1
	v_permlane32_swap_b32 v84, v85
	s_nop 1
	s_nop 0
	v_max_f32_e32 v85, v85, v85
	v_max_f32_e32 v84, v84, v84
	v_max_f32_e32 v84, v84, v85
	v_cmp_lt_f32_e32 vcc, s56, v84
	s_cmp_lg_u64 vcc, 0
	s_cselect_b64 s[2:3], -1, 0
	s_cbranch_vccz .LBB0_464
	v_max_f32_e32 v0, v84, v84
	v_max_f32_e32 v84, 0, v0
	v_exp_f32_e64 v0, -v84
	v_add_f32_e32 v199, v199, v84
	v_pk_add_f32 v[98:99], v[98:99], v[84:85] op_sel_hi:[1,0] neg_lo:[0,1] neg_hi:[0,1]
	v_pk_add_f32 v[114:115], v[114:115], v[84:85] op_sel_hi:[1,0] neg_lo:[0,1] neg_hi:[0,1]
	v_pk_add_f32 v[100:101], v[100:101], v[84:85] op_sel_hi:[1,0] neg_lo:[0,1] neg_hi:[0,1]
	v_pk_add_f32 v[116:117], v[116:117], v[84:85] op_sel_hi:[1,0] neg_lo:[0,1] neg_hi:[0,1]
	v_pk_add_f32 v[102:103], v[102:103], v[84:85] op_sel_hi:[1,0] neg_lo:[0,1] neg_hi:[0,1]
	v_pk_add_f32 v[118:119], v[118:119], v[84:85] op_sel_hi:[1,0] neg_lo:[0,1] neg_hi:[0,1]
	v_pk_add_f32 v[104:105], v[104:105], v[84:85] op_sel_hi:[1,0] neg_lo:[0,1] neg_hi:[0,1]
	v_pk_add_f32 v[120:121], v[120:121], v[84:85] op_sel_hi:[1,0] neg_lo:[0,1] neg_hi:[0,1]
	v_pk_add_f32 v[106:107], v[106:107], v[84:85] op_sel_hi:[1,0] neg_lo:[0,1] neg_hi:[0,1]
	v_pk_add_f32 v[122:123], v[122:123], v[84:85] op_sel_hi:[1,0] neg_lo:[0,1] neg_hi:[0,1]
	v_pk_add_f32 v[108:109], v[108:109], v[84:85] op_sel_hi:[1,0] neg_lo:[0,1] neg_hi:[0,1]
	v_pk_add_f32 v[124:125], v[124:125], v[84:85] op_sel_hi:[1,0] neg_lo:[0,1] neg_hi:[0,1]
	v_pk_add_f32 v[110:111], v[110:111], v[84:85] op_sel_hi:[1,0] neg_lo:[0,1] neg_hi:[0,1]
	v_pk_add_f32 v[126:127], v[126:127], v[84:85] op_sel_hi:[1,0] neg_lo:[0,1] neg_hi:[0,1]
	v_pk_add_f32 v[112:113], v[112:113], v[84:85] op_sel_hi:[1,0] neg_lo:[0,1] neg_hi:[0,1]
	v_pk_add_f32 v[128:129], v[128:129], v[84:85] op_sel_hi:[1,0] neg_lo:[0,1] neg_hi:[0,1]
	v_mul_f32_e32 v179, v179, v0
	s_branch .LBB0_464
